# placement check: whole post-P0 instruction stream shifted by +16 bytes (same 8-byte phase, different 64-byte phase of every loop head)
# baseline (speedup 1.0000x reference)
; __global__ void __launch_bounds__(512, 2) fwd_megakernel(Args args) {
;     ...
;     float* MOD = (float*)(ws + WS_MOD); float* CTXS = (float*)(ws + WS_CTXS);
;     bf16_t* W256 = (bf16_t*)(ws + WS_W256); bf16_t* CS256 = (bf16_t*)(ws + WS_CS256); float* AT = (float*)(ws + WS_AT);
;     bf16_t* WINT = (bf16_t*)(ws + WS_WINT); bf16_t* WOUTT = (bf16_t*)(ws + WS_WOUTT); bf16_t* WGLUT = (bf16_t*)(ws + WS_WGLUT); bf16_t* WFT = (bf16_t*)(ws + WS_WFT);
;     bf16_t* W13T = (bf16_t*)(ws + WS_W13T); bf16_t* W2T = (bf16_t*)(ws + WS_W2T); bf16_t* TC = (bf16_t*)(ws + WS_TC); bf16_t* BS = (bf16_t*)(ws + WS_BS);
;     ...
;         const Ctx X = mkctx(lds);
;         float* scr = (float*)(lds + X.wave * 16384);
;         constexpr int I13 = 16 * 88, I2 = 44 * 32, IIN = 16 * 40, IO = 16 * 32, IG = 8 * 16;
;         constexpr int NITEMS = 8 * I13 + 4 * I2 + IIN + IO + IG + IO;
;         const bool ssmblk = X.G >= 64 && X.bx >= X.G - 32;
;         const int GW = X.G >= 64 ? X.G - 32 : X.G;
;         if (!ssmblk) {
;         for (int it = X.gw; it < NITEMS; it += GW * 8) {
;             int r = it;
;             if (r < 8 * I13) { const int which = r / (4 * I13); r %= 4 * I13; const int lh = r / I13; r %= I13;
;                 if (which == 0) tr_item<1>(args.in[7] + (size_t)lh * D * FF, D, FF, W13T + (size_t)lh * NUP * D, scr, r, X.lane);
;                 else tr_item<2>(args.in[8] + (size_t)lh * D * FF, D, FF, W13T + (size_t)lh * NUP * D, scr, r, X.lane);
;                 continue; }
;             r -= 8 * I13;
;             if (r < 4 * I2) { const int lh = r / I2; r %= I2; tr_item<0>(args.in[9] + (size_t)lh * FF * D, FF, D, W2T + (size_t)lh * D * FF, scr, r, X.lane); continue; }
;             r -= 4 * I2;
;             if (r < IIN) { tr_item<0>(args.in[10], D, INW, WINT, scr, r, X.lane); continue; } r -= IIN;
;             if (r < IO) { tr_item<0>(args.in[23], D, D, WOUTT, scr, r, X.lane); continue; } r -= IO;
;             if (r < IG) { tr_item<0>(args.in[22], 512, 512, WGLUT, scr, r, X.lane); continue; } r -= IG;
;             tr_item<0>(args.in[24], D, D, WFT, scr, r, X.lane);
;         }
.LBB0_6:
	s_nop 0
	s_nop 0
	s_nop 0
	s_nop 0
	s_load_dwordx16 s[36:51], s[0:1], 0x0
	s_add_u32 s0, s88, 0xa00000
	v_writelane_b32 v254, s8, 2
	s_addc_u32 s1, s89, 0
	s_add_u32 s96, s88, 0xb00000
	v_writelane_b32 v254, s9, 3
	v_writelane_b32 v254, s0, 4
	s_addc_u32 s97, s89, 0
	v_mov_b32_e32 v112, v206
	v_writelane_b32 v254, s1, 5
	s_add_u32 s0, s88, 0xe00000
	s_addc_u32 s1, s89, 0
	v_writelane_b32 v254, s0, 6
	s_nop 0
	v_readfirstlane_b32 s3, v112
	v_writelane_b32 v254, s1, 7
	s_add_u32 s0, s88, 0x1000000
	s_addc_u32 s1, s89, 0
	v_writelane_b32 v254, s0, 8
	v_and_b32_e32 v2, 63, v112
	s_nop 0
	v_writelane_b32 v254, s1, 9
	s_add_u32 s0, s88, 0x1100000
	s_addc_u32 s1, s89, 0
	s_add_u32 s95, s88, 0x1300000
	v_writelane_b32 v254, s0, 10
	s_addc_u32 s30, s89, 0
	s_nop 0
	v_writelane_b32 v254, s1, 11
	s_add_u32 s0, s88, 0x3f00000
	v_writelane_b32 v254, s0, 12
	s_addc_u32 s0, s89, 0
	v_writelane_b32 v254, s0, 13
	s_lshl_b32 s0, s2, 3
	s_cmp_gt_i32 s90, 63
	s_cselect_b64 s[12:13], -1, 0
	s_sub_i32 s18, s90, 32
	s_cmp_ge_i32 s2, s18
	v_writelane_b32 v254, s0, 14
	s_cselect_b64 s[0:1], -1, 0
	s_and_b64 s[0:1], s[12:13], s[0:1]
	s_ashr_i32 s28, s3, 6
	s_andn2_b64 vcc, exec, s[0:1]
	s_mov_b64 s[0:1], -1
	v_writelane_b32 v254, s93, 15
	s_cbranch_vccz .LBB0_54
	v_writelane_b32 v254, s12, 16
	s_and_b64 s[0:1], s[12:13], exec
	s_mov_b32 s0, s18
	v_writelane_b32 v254, s13, 17
	v_writelane_b32 v254, s0, 18
	s_cselect_b32 s3, s18, s90
	s_nop 0
	v_writelane_b32 v254, s1, 19
	s_nop 0
	v_readlane_b32 s0, v254, 14
	s_add_i32 s13, s28, s0
	s_cmpk_gt_i32 s13, 0x48ff
	s_cbranch_scc1 .LBB0_33
	v_lshlrev_b32_e32 v10, 3, v2
	s_lshl_b32 s0, s28, 14
	v_lshrrev_b32_e32 v1, 5, v2
	v_and_b32_e32 v4, 31, v112
	v_lshrrev_b32_e32 v5, 3, v2
	v_and_b32_e32 v10, 56, v10
	s_add_i32 s0, s0, 0
	v_lshlrev_b32_e32 v6, 2, v4
	v_mul_u32_u24_e32 v3, 0x84, v1
	v_mul_u32_u24_e32 v14, 0x84, v10
	v_lshlrev_b32_e32 v26, 2, v5
	v_mov_b32_e32 v7, 0
	v_add3_u32 v3, s0, v3, v6
	v_add3_u32 v30, s0, v14, v26
	v_readlane_b32 s0, v254, 8
	v_lshlrev_b32_e32 v24, 1, v10
	v_mov_b32_e32 v25, v7
	v_readlane_b32 s1, v254, 9
	v_and_b32_e32 v11, 16, v26
	v_readlane_b32 s4, v254, 10
	v_lshl_add_u64 v[16:17], s[0:1], 0, v[24:25]
	v_readlane_b32 s0, v254, 6
	v_readlane_b32 s1, v254, 7
	v_readlane_b32 s5, v254, 11
	v_or_b32_e32 v31, v5, v26
	v_lshl_add_u64 v[20:21], s[0:1], 0, v[24:25]
	s_lshl_b32 s0, s2, 4
	s_lshl_b32 s1, s28, 1
	s_add_i32 s0, s0, s1
	v_or_b32_e32 v32, v11, v5
	s_add_i32 s15, s0, 0x17200
	s_lshl_b32 s0, s2, 5
	s_lshl_b32 s1, s28, 2
	s_lshl_b32 s14, s3, 3
	v_lshl_add_u64 v[8:9], s[84:85], 0, v[6:7]
	v_lshl_add_u64 v[12:13], s[4:5], 0, v[24:25]
	v_lshl_add_u64 v[14:15], s[80:81], 0, v[6:7]
	v_lshl_add_u64 v[18:19], s[82:83], 0, v[6:7]
	v_lshl_add_u64 v[22:23], s[56:57], 0, v[6:7]
	v_lshl_add_u64 v[24:25], s[96:97], 0, v[24:25]
	v_bitop3_b32 v33, v5, 19, v26 bitop3:0xc8
	v_or_b32_e32 v34, 0x8c, v26
	v_or_b32_e32 v35, 12, v26
	v_or_b32_e32 v36, 4, v32
	v_or_b32_e32 v37, 12, v31
	s_lshl_b32 s16, s3, 4
	s_add_i32 s17, s0, s1
	s_lshl_b32 s18, s3, 5
	s_movk_i32 s94, 0x2000
	s_movk_i32 s93, 0x4000
	s_mov_b32 s26, 0x10000
	s_mov_b32 s31, 0x16000
	v_add_u32_e32 v38, 0x400, v3
	v_add_u32_e32 v39, 0x800, v3
	v_add_u32_e32 v40, 0xc00, v3
	v_add_u32_e32 v41, 0x1000, v3
	v_add_u32_e32 v42, 0x1400, v3
	v_add_u32_e32 v43, 0x1800, v3
	v_add_u32_e32 v44, 0x1c00, v3
	v_mov_b32_e32 v45, 0x2000
	v_mov_b32_e32 v46, 0x6000
	v_mov_b32_e32 v47, 0x200
	v_mov_b32_e32 v48, 0x1000
	v_mov_b32_e32 v49, 0x3000
	v_mov_b32_e32 v50, 0x63
	s_mov_b32 s83, 0x26000
	s_mov_b32 s21, 0x2c000
	s_mov_b32 s27, 0x3c000
	s_movk_i32 s57, 0x5000
	s_mov_b32 s80, 0xb000
	s_mov_b32 s10, 0x1b000
	s_mov_b32 s11, 0x37000
	s_mov_b32 s82, 0x4d000
	s_mov_b32 s19, 0x6e000
	s_mov_b32 s12, 0x73000
	s_mov_b32 s20, 0x79000
	s_mov_b32 s84, 0x7e000
	s_mov_b32 s85, 0x84000
	s_mov_b32 s22, 0x89000
	s_mov_b32 s25, 0x8f000
	s_mov_b32 s56, 0x94000
	s_mov_b32 s23, 0x9a000
	s_mov_b32 s24, 0x9f000
	s_mov_b32 s29, 0xa5000
	s_mov_b32 s81, 0xaa000
	s_mov_b32 s1, 0
	s_branch .LBB0_10
